# softmax row sums start from p0+p1 instead of 0+p0 in the MLA loop and the NA local tiles (one VALU less per query group per tile)
# baseline (speedup 1.0000x reference)
.Lna_l0_keep1:
	s_waitcnt lgkmcnt(6)
	ds_read_b64_tr_b16 v[180:181], v160 offset:18496
	ds_read_b64_tr_b16 v[182:183], v160 offset:20800
	ds_read_b64_tr_b16 v[184:185], v160 offset:18528
	ds_read_b64_tr_b16 v[186:187], v160 offset:20832
	ds_read_b64_tr_b16 v[154:155], v160 offset:23104
	ds_read_b64_tr_b16 v[156:157], v160 offset:25408
	ds_read_b64_tr_b16 v[200:201], v160 offset:23136
	ds_read_b64_tr_b16 v[202:203], v160 offset:25440
	v_sub_f32_e32 v224, v224, v144
	v_sub_f32_e32 v225, v225, v144
	v_exp_f32_e32 v224, v224
	v_sub_f32_e32 v226, v226, v144
	v_exp_f32_e32 v225, v225
	v_sub_f32_e32 v227, v227, v144
	v_exp_f32_e32 v226, v226
	v_exp_f32_e32 v227, v227
	v_sub_f32_e32 v228, v228, v144
	v_sub_f32_e32 v229, v229, v144
	v_exp_f32_e32 v228, v228
	v_sub_f32_e32 v230, v230, v144
	v_exp_f32_e32 v229, v229
	v_sub_f32_e32 v231, v231, v144
	v_exp_f32_e32 v230, v230
	v_exp_f32_e32 v231, v231
	v_add_f32_e32 v246, v225, v224
	v_add_f32_e32 v246, v226, v246
	v_add_f32_e32 v246, v227, v246
	v_cvt_pk_bf16_f32 v66, v224, v225
	v_cvt_pk_bf16_f32 v67, v226, v227
	v_add_f32_e32 v246, v228, v246
	v_add_f32_e32 v246, v229, v246
	v_add_f32_e32 v246, v230, v246
	v_add_f32_e32 v246, v231, v246
	v_cvt_pk_bf16_f32 v68, v228, v229
	v_cvt_pk_bf16_f32 v69, v230, v231
	v_add_f32_e32 v140, v140, v246
	s_nop 0
	v_mfma_f32_16x16x32_bf16 v[18:21], v[164:167], v[66:69], v[18:21]
	v_sub_f32_e32 v232, v232, v142
	v_sub_f32_e32 v233, v233, v142
	v_exp_f32_e32 v232, v232
	v_sub_f32_e32 v234, v234, v142
	v_exp_f32_e32 v233, v233
	v_sub_f32_e32 v235, v235, v142
	v_exp_f32_e32 v234, v234
	v_exp_f32_e32 v235, v235
	v_sub_f32_e32 v236, v236, v142
	v_sub_f32_e32 v237, v237, v142
	v_exp_f32_e32 v236, v236
	s_waitcnt lgkmcnt(12)
	v_mfma_f32_16x16x32_bf16 v[22:25], v[168:171], v[66:69], v[22:25]
	v_sub_f32_e32 v238, v238, v142
	v_exp_f32_e32 v237, v237
	v_sub_f32_e32 v239, v239, v142
	v_exp_f32_e32 v238, v238
	v_exp_f32_e32 v239, v239
	v_add_f32_e32 v247, v233, v232
	v_add_f32_e32 v247, v234, v247
	v_add_f32_e32 v247, v235, v247
	v_cvt_pk_bf16_f32 v74, v232, v233
	v_cvt_pk_bf16_f32 v75, v234, v235
	v_sub_f32_e32 v240, v240, v142
	s_waitcnt lgkmcnt(6)
	v_mfma_f32_16x16x32_bf16 v[10:13], v[180:183], v[66:69], v[10:13]
	v_sub_f32_e32 v241, v241, v142
	v_exp_f32_e32 v240, v240
	v_sub_f32_e32 v242, v242, v142
	v_exp_f32_e32 v241, v241
	v_sub_f32_e32 v243, v243, v142
	v_exp_f32_e32 v242, v242
	v_exp_f32_e32 v243, v243
	v_add_f32_e32 v247, v236, v247
	v_add_f32_e32 v247, v237, v247
	v_add_f32_e32 v247, v238, v247
	v_add_f32_e32 v247, v239, v247
	s_waitcnt lgkmcnt(4)
	v_mfma_f32_16x16x32_bf16 v[2:5], v[184:187], v[66:69], v[2:5]
	v_cvt_pk_bf16_f32 v76, v236, v237
	v_cvt_pk_bf16_f32 v77, v238, v239
	v_add_f32_e32 v247, v240, v247
	v_add_f32_e32 v247, v241, v247
	v_add_f32_e32 v247, v242, v247
	v_add_f32_e32 v247, v243, v247
	v_cvt_pk_bf16_f32 v78, v240, v241
	v_cvt_pk_bf16_f32 v79, v242, v243
	v_mov_b32_e32 v80, 0
	v_mov_b32_e32 v81, 0
	v_add_f32_e32 v137, v137, v247
	v_mfma_f32_16x16x32_bf16 v[30:33], v[164:167], v[74:77], v[30:33]
	v_mfma_f32_16x16x32_bf16 v[26:29], v[168:171], v[74:77], v[26:29]
	v_mfma_f32_16x16x32_bf16 v[30:33], v[172:175], v[78:81], v[30:33]
	v_mfma_f32_16x16x32_bf16 v[26:29], v[176:179], v[78:81], v[26:29]
	v_mfma_f32_16x16x32_bf16 v[14:17], v[180:183], v[74:77], v[14:17]
	v_mfma_f32_16x16x32_bf16 v[6:9], v[184:187], v[74:77], v[6:9]
	s_waitcnt lgkmcnt(2)
	v_mfma_f32_16x16x32_bf16 v[14:17], v[154:157], v[78:81], v[14:17]
	s_waitcnt lgkmcnt(0)
	v_mfma_f32_16x16x32_bf16 v[6:9], v[200:203], v[78:81], v[6:9]
	s_branch .LBB0_337

.Lna_l1_keep1:
	s_waitcnt lgkmcnt(6)
	ds_read_b64_tr_b16 v[180:181], v160 offset:18496
	ds_read_b64_tr_b16 v[182:183], v160 offset:20800
	ds_read_b64_tr_b16 v[184:185], v160 offset:18528
	ds_read_b64_tr_b16 v[186:187], v160 offset:20832
	ds_read_b64_tr_b16 v[154:155], v160 offset:23104
	ds_read_b64_tr_b16 v[156:157], v160 offset:25408
	ds_read_b64_tr_b16 v[200:201], v160 offset:23136
	ds_read_b64_tr_b16 v[202:203], v160 offset:25440
	v_sub_f32_e32 v224, v224, v144
	v_sub_f32_e32 v225, v225, v144
	v_exp_f32_e32 v224, v224
	v_sub_f32_e32 v226, v226, v144
	v_exp_f32_e32 v225, v225
	v_sub_f32_e32 v227, v227, v144
	v_exp_f32_e32 v226, v226
	v_exp_f32_e32 v227, v227
	v_mov_b32_e32 v66, 0
	v_mov_b32_e32 v67, 0
	v_sub_f32_e32 v228, v228, v144
	v_sub_f32_e32 v229, v229, v144
	v_exp_f32_e32 v228, v228
	v_sub_f32_e32 v230, v230, v144
	v_exp_f32_e32 v229, v229
	v_sub_f32_e32 v231, v231, v144
	v_exp_f32_e32 v230, v230
	v_exp_f32_e32 v231, v231
	v_add_f32_e32 v246, v225, v224
	v_add_f32_e32 v246, v226, v246
	v_add_f32_e32 v246, v227, v246
	v_cvt_pk_bf16_f32 v68, v224, v225
	v_cvt_pk_bf16_f32 v69, v226, v227
	v_sub_f32_e32 v232, v232, v144
	v_sub_f32_e32 v233, v233, v144
	v_exp_f32_e32 v232, v232
	v_sub_f32_e32 v234, v234, v144
	v_exp_f32_e32 v233, v233
	v_sub_f32_e32 v235, v235, v144
	v_exp_f32_e32 v234, v234
	v_exp_f32_e32 v235, v235
	v_add_f32_e32 v246, v228, v246
	v_add_f32_e32 v246, v229, v246
	v_add_f32_e32 v246, v230, v246
	v_add_f32_e32 v246, v231, v246
	v_cvt_pk_bf16_f32 v70, v228, v229
	v_cvt_pk_bf16_f32 v71, v230, v231
	v_add_f32_e32 v246, v232, v246
	v_add_f32_e32 v246, v233, v246
	v_add_f32_e32 v246, v234, v246
	v_add_f32_e32 v246, v235, v246
	v_cvt_pk_bf16_f32 v72, v232, v233
	v_cvt_pk_bf16_f32 v73, v234, v235
	v_add_f32_e32 v140, v140, v246
	v_mfma_f32_16x16x32_bf16 v[18:21], v[164:167], v[66:69], v[18:21]
	v_sub_f32_e32 v236, v236, v142
	v_sub_f32_e32 v237, v237, v142
	v_exp_f32_e32 v236, v236
	v_sub_f32_e32 v238, v238, v142
	s_waitcnt lgkmcnt(12)
	v_mfma_f32_16x16x32_bf16 v[22:25], v[168:171], v[66:69], v[22:25]
	v_exp_f32_e32 v237, v237
	v_sub_f32_e32 v239, v239, v142
	v_exp_f32_e32 v238, v238
	v_exp_f32_e32 v239, v239
	s_waitcnt lgkmcnt(10)
	v_mfma_f32_16x16x32_bf16 v[18:21], v[172:175], v[70:73], v[18:21]
	v_sub_f32_e32 v240, v240, v142
	v_sub_f32_e32 v241, v241, v142
	v_exp_f32_e32 v240, v240
	v_sub_f32_e32 v242, v242, v142
	s_waitcnt lgkmcnt(8)
	v_mfma_f32_16x16x32_bf16 v[22:25], v[176:179], v[70:73], v[22:25]
	v_exp_f32_e32 v241, v241
	v_sub_f32_e32 v243, v243, v142
	v_exp_f32_e32 v242, v242
	v_exp_f32_e32 v243, v243
	s_waitcnt lgkmcnt(6)
	v_mfma_f32_16x16x32_bf16 v[10:13], v[180:183], v[66:69], v[10:13]
	v_add_f32_e32 v247, v237, v236
	v_add_f32_e32 v247, v238, v247
	v_add_f32_e32 v247, v239, v247
	v_cvt_pk_bf16_f32 v78, v236, v237
	s_waitcnt lgkmcnt(4)
	v_mfma_f32_16x16x32_bf16 v[2:5], v[184:187], v[66:69], v[2:5]
	v_cvt_pk_bf16_f32 v79, v238, v239
	v_add_f32_e32 v247, v240, v247
	v_add_f32_e32 v247, v241, v247
	v_add_f32_e32 v247, v242, v247
	s_waitcnt lgkmcnt(2)
	v_mfma_f32_16x16x32_bf16 v[10:13], v[154:157], v[70:73], v[10:13]
	v_add_f32_e32 v247, v243, v247
	v_cvt_pk_bf16_f32 v80, v240, v241
	v_cvt_pk_bf16_f32 v81, v242, v243
	v_add_f32_e32 v137, v137, v247
	s_waitcnt lgkmcnt(0)
	v_mfma_f32_16x16x32_bf16 v[2:5], v[200:203], v[70:73], v[2:5]
	v_mfma_f32_16x16x32_bf16 v[30:33], v[172:175], v[78:81], v[30:33]
	v_mfma_f32_16x16x32_bf16 v[26:29], v[176:179], v[78:81], v[26:29]
	v_mfma_f32_16x16x32_bf16 v[14:17], v[154:157], v[78:81], v[14:17]
	v_mfma_f32_16x16x32_bf16 v[6:9], v[200:203], v[78:81], v[6:9]
	s_branch .LBB0_337
